# v19: + rs=v_rsq_f32 instead of expanded IEEE sqrt+div in the RS epilogues (P6/P10), on top of v16
# speedup vs baseline: 1.0071x; 1.0071x over previous
; __device__ __forceinline__ void st8(bf16_t* p, const f32x4& a, const f32x4& b) { u32x4 w; w.x = pk2(a[0], a[1]); w.y = pk2(a[2], a[3]); w.z = pk2(b[0], b[1]); w.w = pk2(b[2], b[3]); *(u32x4*)p = w; }
;     __device__ __forceinline__ void operator()(const f32x4 (&acc)[2][2][4][2], const Unit& u, int wr, int wc, int fr, int fq) const {
;         const int row0 = u.pm * 256 + wr * 64 + fr, col0 = u.pn * 256 + wc * 32 + 8 * fq;
; #pragma unroll
;         for (int ai = 0; ai < 2; ++ai)
; #pragma unroll
;             for (int m = 0; m < 4; ++m) {
;                 const int row = row0 + ai * 128 + m * 16; const float rs = sc * (1.0f / sqrtf(ssq[row] * (1.f / D) + RMS_EPS));
;                 bf16_t* rp = O + (size_t)row * ldc + col0;
; #pragma unroll
;                 for (int bj = 0; bj < 2; ++bj) st8(rp + bj * 128, acc[ai][bj][m][0] * rs, acc[ai][bj][m][1] * rs);
;             }
;     }
.LBB0_737:
	v_lshl_add_u32 v152, s4, 8, v1
	v_ashrrev_i32_e32 v153, 31, v152
	v_lshl_add_u64 v[148:149], v[152:153], 2, s[14:15]
	global_load_dword v150, v[148:149], off
	global_load_dword v170, v[148:149], off offset:64
	global_load_dword v171, v[148:149], off offset:128
	global_load_dword v172, v[148:149], off offset:192
	global_load_dword v173, v[148:149], off offset:512
	global_load_dword v174, v[148:149], off offset:576
	global_load_dword v175, v[148:149], off offset:640
	global_load_dword v176, v[148:149], off offset:704
	v_lshl_or_b32 v146, s5, 8, v155
	v_ashrrev_i32_e32 v147, 31, v146
	v_lshlrev_b64 v[162:163], 10, v[152:153]
	s_mov_b32 s24, 0x20000
	s_waitcnt vmcnt(0)
	v_fmamk_f32 v150, v150, 0x3a000000, v159
	v_rsq_f32_e32 v253, v150
	s_nop 1
	v_lshlrev_b64 v[150:151], 1, v[146:147]
	v_lshl_add_u64 v[146:147], s[6:7], 0, v[162:163]
	v_lshl_add_u64 v[146:147], v[146:147], 0, v[150:151]
	s_nop 1
	s_nop 1
	s_nop 1
	s_nop 0
	v_mov_b32_e32 v153, v253
	v_mul_f32_e32 v162, 0x3e0293ee, v153
	v_pk_mul_f32 v[128:129], v[128:129], v[162:163] op_sel_hi:[1,0]
	v_pk_mul_f32 v[126:127], v[126:127], v[162:163] op_sel_hi:[1,0]
	v_pk_mul_f32 v[124:125], v[124:125], v[162:163] op_sel_hi:[1,0]
	v_pk_mul_f32 v[122:123], v[122:123], v[162:163] op_sel_hi:[1,0]
	v_pk_mul_f32 v[120:121], v[120:121], v[162:163] op_sel_hi:[1,0]
	v_pk_mul_f32 v[118:119], v[118:119], v[162:163] op_sel_hi:[1,0]
	v_pk_mul_f32 v[164:165], v[116:117], v[162:163] op_sel_hi:[1,0]
	v_pk_mul_f32 v[162:163], v[114:115], v[162:163] op_sel_hi:[1,0]
	v_cvt_pk_bf16_f32 v114, v126, v127
	v_cvt_pk_bf16_f32 v115, v128, v129
	v_cvt_pk_bf16_f32 v116, v122, v123
	v_cvt_pk_bf16_f32 v117, v124, v125
	global_store_dwordx4 v[146:147], v[114:117], off
	s_nop 1
	v_cvt_pk_bf16_f32 v114, v118, v119
	v_cvt_pk_bf16_f32 v115, v120, v121
	v_cvt_pk_bf16_f32 v116, v162, v163
	v_cvt_pk_bf16_f32 v117, v164, v165
	global_store_dwordx4 v[146:147], v[114:117], off offset:256
	s_nop 1
	v_mov_b32_e32 v115, v170
	s_nop 0
	v_or_b32_e32 v114, 16, v152
	v_fmamk_f32 v115, v115, 0x3a000000, v159
	v_rsq_f32_e32 v253, v115
	s_nop 1
	v_ashrrev_i32_e32 v115, 31, v114
	v_lshlrev_b64 v[114:115], 10, v[114:115]
	v_lshl_add_u64 v[114:115], s[6:7], 0, v[114:115]
	v_lshl_add_u64 v[114:115], v[114:115], 0, v[150:151]
	s_nop 0
	s_nop 1
	s_nop 1
	s_nop 0
	v_mov_b32_e32 v116, v253
	v_mul_f32_e32 v116, 0x3e0293ee, v116
	v_pk_mul_f32 v[112:113], v[112:113], v[116:117] op_sel_hi:[1,0]
	v_pk_mul_f32 v[110:111], v[110:111], v[116:117] op_sel_hi:[1,0]
	v_pk_mul_f32 v[108:109], v[108:109], v[116:117] op_sel_hi:[1,0]
	v_pk_mul_f32 v[106:107], v[106:107], v[116:117] op_sel_hi:[1,0]
	v_pk_mul_f32 v[104:105], v[104:105], v[116:117] op_sel_hi:[1,0]
	v_pk_mul_f32 v[102:103], v[102:103], v[116:117] op_sel_hi:[1,0]
	v_pk_mul_f32 v[118:119], v[100:101], v[116:117] op_sel_hi:[1,0]
	v_pk_mul_f32 v[116:117], v[98:99], v[116:117] op_sel_hi:[1,0]
	v_cvt_pk_bf16_f32 v98, v110, v111
	v_cvt_pk_bf16_f32 v99, v112, v113
	v_cvt_pk_bf16_f32 v100, v106, v107
	v_cvt_pk_bf16_f32 v101, v108, v109
	global_store_dwordx4 v[114:115], v[98:101], off
	s_nop 1
	v_cvt_pk_bf16_f32 v98, v102, v103
	v_cvt_pk_bf16_f32 v99, v104, v105
	v_cvt_pk_bf16_f32 v100, v116, v117
	v_cvt_pk_bf16_f32 v101, v118, v119
	global_store_dwordx4 v[114:115], v[98:101], off offset:256
	s_nop 1
	v_mov_b32_e32 v99, v171
	s_nop 0
	v_or_b32_e32 v98, 32, v152
	v_fmamk_f32 v99, v99, 0x3a000000, v159
	v_rsq_f32_e32 v253, v99
	s_nop 1
	v_ashrrev_i32_e32 v99, 31, v98
	v_lshlrev_b64 v[98:99], 10, v[98:99]
	v_lshl_add_u64 v[98:99], s[6:7], 0, v[98:99]
	v_lshl_add_u64 v[98:99], v[98:99], 0, v[150:151]
	s_nop 0
	s_nop 1
	s_nop 1
	s_nop 0
	v_mov_b32_e32 v100, v253
	v_mul_f32_e32 v100, 0x3e0293ee, v100
	v_pk_mul_f32 v[96:97], v[96:97], v[100:101] op_sel_hi:[1,0]
	v_pk_mul_f32 v[94:95], v[94:95], v[100:101] op_sel_hi:[1,0]
	v_pk_mul_f32 v[92:93], v[92:93], v[100:101] op_sel_hi:[1,0]
	v_pk_mul_f32 v[90:91], v[90:91], v[100:101] op_sel_hi:[1,0]
	v_pk_mul_f32 v[88:89], v[88:89], v[100:101] op_sel_hi:[1,0]
	v_pk_mul_f32 v[86:87], v[86:87], v[100:101] op_sel_hi:[1,0]
	v_pk_mul_f32 v[102:103], v[84:85], v[100:101] op_sel_hi:[1,0]
	v_pk_mul_f32 v[100:101], v[82:83], v[100:101] op_sel_hi:[1,0]
	v_cvt_pk_bf16_f32 v82, v94, v95
	v_cvt_pk_bf16_f32 v83, v96, v97
	v_cvt_pk_bf16_f32 v84, v90, v91
	v_cvt_pk_bf16_f32 v85, v92, v93
	global_store_dwordx4 v[98:99], v[82:85], off
	s_nop 1
	v_cvt_pk_bf16_f32 v82, v86, v87
	v_cvt_pk_bf16_f32 v83, v88, v89
	v_cvt_pk_bf16_f32 v84, v100, v101
	v_cvt_pk_bf16_f32 v85, v102, v103
	global_store_dwordx4 v[98:99], v[82:85], off offset:256
	s_nop 1
	v_mov_b32_e32 v83, v172
	s_nop 0
	v_or_b32_e32 v82, 48, v152
	v_fmamk_f32 v83, v83, 0x3a000000, v159
	v_rsq_f32_e32 v253, v83
	s_nop 1
	v_ashrrev_i32_e32 v83, 31, v82
	v_lshlrev_b64 v[82:83], 10, v[82:83]
	v_lshl_add_u64 v[82:83], s[6:7], 0, v[82:83]
	v_lshl_add_u64 v[82:83], v[82:83], 0, v[150:151]
	s_nop 0
	s_nop 1
	s_nop 1
	s_mov_b64 s[4:5], 0x20000
	s_nop 0
	v_mov_b32_e32 v84, v253
	v_mul_f32_e32 v84, 0x3e0293ee, v84
	v_pk_mul_f32 v[80:81], v[80:81], v[84:85] op_sel_hi:[1,0]
	v_pk_mul_f32 v[78:79], v[78:79], v[84:85] op_sel_hi:[1,0]
	v_pk_mul_f32 v[76:77], v[76:77], v[84:85] op_sel_hi:[1,0]
	v_pk_mul_f32 v[74:75], v[74:75], v[84:85] op_sel_hi:[1,0]
	v_pk_mul_f32 v[72:73], v[72:73], v[84:85] op_sel_hi:[1,0]
	v_pk_mul_f32 v[70:71], v[70:71], v[84:85] op_sel_hi:[1,0]
	v_pk_mul_f32 v[86:87], v[68:69], v[84:85] op_sel_hi:[1,0]
; __device__ __forceinline__ void st8(bf16_t* p, const f32x4& a, const f32x4& b) { u32x4 w; w.x = pk2(a[0], a[1]); w.y = pk2(a[2], a[3]); w.z = pk2(b[0], b[1]); w.w = pk2(b[2], b[3]); *(u32x4*)p = w; }
;     __device__ __forceinline__ void operator()(const f32x4 (&acc)[2][2][4][2], const Unit& u, int wr, int wc, int fr, int fq) const {
;         const int row0 = u.pm * 256 + wr * 64 + fr, col0 = u.pn * 256 + wc * 32 + 8 * fq;
; #pragma unroll
;         for (int ai = 0; ai < 2; ++ai)
; #pragma unroll
;             for (int m = 0; m < 4; ++m) {
;                 const int row = row0 + ai * 128 + m * 16; const float rs = sc * (1.0f / sqrtf(ssq[row] * (1.f / D) + RMS_EPS));
;                 bf16_t* rp = O + (size_t)row * ldc + col0;
; #pragma unroll
;                 for (int bj = 0; bj < 2; ++bj) st8(rp + bj * 128, acc[ai][bj][m][0] * rs, acc[ai][bj][m][1] * rs);
;             }
;     }
	v_pk_mul_f32 v[84:85], v[66:67], v[84:85] op_sel_hi:[1,0]
	v_cvt_pk_bf16_f32 v66, v78, v79
	v_cvt_pk_bf16_f32 v67, v80, v81
	v_cvt_pk_bf16_f32 v68, v74, v75
	v_cvt_pk_bf16_f32 v69, v76, v77
	global_store_dwordx4 v[82:83], v[66:69], off
	s_nop 1
	v_cvt_pk_bf16_f32 v66, v70, v71
	v_cvt_pk_bf16_f32 v67, v72, v73
	v_cvt_pk_bf16_f32 v68, v84, v85
	v_cvt_pk_bf16_f32 v69, v86, v87
	global_store_dwordx4 v[82:83], v[66:69], off offset:256
	s_nop 1
	v_mov_b32_e32 v66, v173
	v_fmamk_f32 v66, v66, 0x3a000000, v159
	v_rsq_f32_e32 v253, v66
	s_nop 1
	v_lshl_add_u64 v[66:67], v[146:147], 0, s[4:5]
	s_nop 1
	s_nop 1
	s_nop 1
	v_add_co_u32_e32 v68, vcc, s24, v146
	s_mov_b64 s[4:5], 0x24000
	s_nop 0
	v_addc_co_u32_e32 v69, vcc, 0, v147, vcc
	s_nop 0
	v_mov_b32_e32 v70, v253
	v_mul_f32_e32 v70, 0x3e0293ee, v70
	v_pk_mul_f32 v[64:65], v[64:65], v[70:71] op_sel_hi:[1,0]
	v_pk_mul_f32 v[62:63], v[62:63], v[70:71] op_sel_hi:[1,0]
	v_pk_mul_f32 v[60:61], v[60:61], v[70:71] op_sel_hi:[1,0]
	v_pk_mul_f32 v[58:59], v[58:59], v[70:71] op_sel_hi:[1,0]
	v_pk_mul_f32 v[56:57], v[56:57], v[70:71] op_sel_hi:[1,0]
	v_pk_mul_f32 v[54:55], v[54:55], v[70:71] op_sel_hi:[1,0]
	v_pk_mul_f32 v[72:73], v[52:53], v[70:71] op_sel_hi:[1,0]
	v_pk_mul_f32 v[70:71], v[50:51], v[70:71] op_sel_hi:[1,0]
	v_cvt_pk_bf16_f32 v50, v62, v63
	v_cvt_pk_bf16_f32 v51, v64, v65
	v_cvt_pk_bf16_f32 v52, v58, v59
	v_cvt_pk_bf16_f32 v53, v60, v61
	global_store_dwordx4 v[68:69], v[50:53], off
	s_mov_b32 s24, 0x24000
	s_nop 0
	v_cvt_pk_bf16_f32 v50, v54, v55
	v_cvt_pk_bf16_f32 v51, v56, v57
	v_cvt_pk_bf16_f32 v52, v70, v71
	v_cvt_pk_bf16_f32 v53, v72, v73
	global_store_dwordx4 v[66:67], v[50:53], off offset:256
	s_nop 1
	v_mov_b32_e32 v50, v174
	v_fmamk_f32 v50, v50, 0x3a000000, v159
	v_rsq_f32_e32 v253, v50
	s_nop 1
	v_lshl_add_u64 v[50:51], v[146:147], 0, s[4:5]
	s_nop 1
	s_nop 1
	s_nop 1
	v_add_co_u32_e32 v52, vcc, s24, v146
	s_mov_b64 s[4:5], 0x28000
	s_nop 0
	v_addc_co_u32_e32 v53, vcc, 0, v147, vcc
	s_nop 0
	v_mov_b32_e32 v54, v253
	v_mul_f32_e32 v54, 0x3e0293ee, v54
	v_pk_mul_f32 v[48:49], v[48:49], v[54:55] op_sel_hi:[1,0]
	v_pk_mul_f32 v[46:47], v[46:47], v[54:55] op_sel_hi:[1,0]
	v_pk_mul_f32 v[44:45], v[44:45], v[54:55] op_sel_hi:[1,0]
	v_pk_mul_f32 v[42:43], v[42:43], v[54:55] op_sel_hi:[1,0]
	v_pk_mul_f32 v[40:41], v[40:41], v[54:55] op_sel_hi:[1,0]
	v_pk_mul_f32 v[38:39], v[38:39], v[54:55] op_sel_hi:[1,0]
	v_pk_mul_f32 v[56:57], v[36:37], v[54:55] op_sel_hi:[1,0]
	v_pk_mul_f32 v[54:55], v[34:35], v[54:55] op_sel_hi:[1,0]
	v_cvt_pk_bf16_f32 v34, v46, v47
	v_cvt_pk_bf16_f32 v35, v48, v49
	v_cvt_pk_bf16_f32 v36, v42, v43
	v_cvt_pk_bf16_f32 v37, v44, v45
	global_store_dwordx4 v[52:53], v[34:37], off
	s_nop 1
	v_cvt_pk_bf16_f32 v34, v38, v39
	v_cvt_pk_bf16_f32 v35, v40, v41
	v_cvt_pk_bf16_f32 v36, v54, v55
	v_cvt_pk_bf16_f32 v37, v56, v57
	global_store_dwordx4 v[50:51], v[34:37], off offset:256
	s_nop 1
	v_mov_b32_e32 v34, v175
	v_fmamk_f32 v34, v34, 0x3a000000, v159
	v_rsq_f32_e32 v253, v34
	s_nop 1
	v_lshl_add_u64 v[34:35], v[146:147], 0, s[4:5]
	s_nop 1
	s_nop 1
	s_nop 1
	v_add_co_u32_e32 v36, vcc, s84, v146
	s_nop 0
	v_addc_co_u32_e32 v37, vcc, 0, v147, vcc
	s_nop 0
	v_mov_b32_e32 v38, v253
	v_mul_f32_e32 v38, 0x3e0293ee, v38
	v_pk_mul_f32 v[32:33], v[32:33], v[38:39] op_sel_hi:[1,0]
	v_pk_mul_f32 v[30:31], v[30:31], v[38:39] op_sel_hi:[1,0]
	v_pk_mul_f32 v[28:29], v[28:29], v[38:39] op_sel_hi:[1,0]
	v_pk_mul_f32 v[26:27], v[26:27], v[38:39] op_sel_hi:[1,0]
	v_pk_mul_f32 v[24:25], v[24:25], v[38:39] op_sel_hi:[1,0]
	v_pk_mul_f32 v[22:23], v[22:23], v[38:39] op_sel_hi:[1,0]
	v_pk_mul_f32 v[40:41], v[20:21], v[38:39] op_sel_hi:[1,0]
	v_pk_mul_f32 v[38:39], v[18:19], v[38:39] op_sel_hi:[1,0]
	v_cvt_pk_bf16_f32 v18, v30, v31
	v_cvt_pk_bf16_f32 v19, v32, v33
	v_cvt_pk_bf16_f32 v20, v26, v27
	v_cvt_pk_bf16_f32 v21, v28, v29
	global_store_dwordx4 v[36:37], v[18:21], off
	s_nop 1
	v_cvt_pk_bf16_f32 v18, v22, v23
	v_cvt_pk_bf16_f32 v19, v24, v25
	v_cvt_pk_bf16_f32 v20, v38, v39
	v_cvt_pk_bf16_f32 v21, v40, v41
	global_store_dwordx4 v[34:35], v[18:21], off offset:256
	s_nop 1
	v_mov_b32_e32 v18, v176
	v_fmamk_f32 v18, v18, 0x3a000000, v159
	v_rsq_f32_e32 v253, v18
	s_nop 1
	v_lshl_add_u64 v[18:19], v[146:147], 0, s[58:59]
	s_nop 1
	s_nop 1
	s_nop 1
	v_add_co_u32_e32 v20, vcc, s85, v146
	s_nop 0
	v_addc_co_u32_e32 v21, vcc, 0, v147, vcc
	s_nop 0
	v_mov_b32_e32 v22, v253
	v_mul_f32_e32 v22, 0x3e0293ee, v22
	s_andn2_b64 vcc, exec, s[2:3]
	v_pk_mul_f32 v[16:17], v[16:17], v[22:23] op_sel_hi:[1,0]
	v_pk_mul_f32 v[14:15], v[14:15], v[22:23] op_sel_hi:[1,0]
	v_pk_mul_f32 v[12:13], v[12:13], v[22:23] op_sel_hi:[1,0]
	v_pk_mul_f32 v[10:11], v[10:11], v[22:23] op_sel_hi:[1,0]
	v_pk_mul_f32 v[8:9], v[8:9], v[22:23] op_sel_hi:[1,0]
	v_pk_mul_f32 v[6:7], v[6:7], v[22:23] op_sel_hi:[1,0]
	v_pk_mul_f32 v[24:25], v[4:5], v[22:23] op_sel_hi:[1,0]
	v_pk_mul_f32 v[22:23], v[2:3], v[22:23] op_sel_hi:[1,0]
	v_cvt_pk_bf16_f32 v2, v14, v15
	v_cvt_pk_bf16_f32 v3, v16, v17
	v_cvt_pk_bf16_f32 v4, v10, v11
	v_cvt_pk_bf16_f32 v5, v12, v13
	s_mov_b64 s[2:3], -1
	global_store_dwordx4 v[20:21], v[2:5], off
	s_nop 1
	v_cvt_pk_bf16_f32 v2, v6, v7
	v_cvt_pk_bf16_f32 v3, v8, v9
	v_cvt_pk_bf16_f32 v4, v22, v23
	v_cvt_pk_bf16_f32 v5, v24, v25
	global_store_dwordx4 v[18:19], v[2:5], off offset:256
	s_cbranch_vccnz .LBB0_726
	s_andn2_b64 vcc, exec, s[52:53]
	s_cbranch_vccnz .LBB0_725
	s_barrier
	s_branch .LBB0_725

; __device__ __forceinline__ float sigm(float x) { return __builtin_amdgcn_rcpf(1.f + __builtin_amdgcn_exp2f(-1.4426950408889634f * x)); }
; __device__ __forceinline__ void st8(bf16_t* p, const f32x4& a, const f32x4& b) { u32x4 w; w.x = pk2(a[0], a[1]); w.y = pk2(a[2], a[3]); w.z = pk2(b[0], b[1]); w.w = pk2(b[2], b[3]); *(u32x4*)p = w; }
;     __device__ __forceinline__ void operator()(const f32x4 (&acc)[2][2][4][2], const Unit& u, int wr, int wc, int fr, int fq) const {
;         const int row0 = u.pm * 256 + wr * 64 + fr, col0 = u.pn * 128 + wc * 32 + 8 * fq;
; #pragma unroll
;         for (int ai = 0; ai < 2; ++ai)
; #pragma unroll
;             for (int m = 0; m < 4; ++m) {
;                 const int row = row0 + ai * 128 + m * 16; const float rs = 1.0f / sqrtf(ssq[row] * (1.f / D) + RMS_EPS);
;                 f32x4 v0, v1;
; #pragma unroll
;                 for (int e = 0; e < 4; ++e) { const float g0 = acc[ai][0][m][0][e] * rs, g1 = acc[ai][0][m][1][e] * rs;
;                     v0[e] = g0 * sigm(g0) * (acc[ai][1][m][0][e] * rs); v1[e] = g1 * sigm(g1) * (acc[ai][1][m][1][e] * rs); }
;                 st8(O + (size_t)row * DFF + col0, v0, v1);
;             }
;     }
.LBB0_1010:
	v_lshl_add_u32 v146, s4, 8, v1
	v_ashrrev_i32_e32 v147, 31, v146
	v_lshl_add_u64 v[148:149], v[146:147], 2, s[6:7]
	global_load_dword v147, v[148:149], off
	global_load_dword v173, v[148:149], off offset:64
	global_load_dword v174, v[148:149], off offset:128
	global_load_dword v175, v[148:149], off offset:192
	global_load_dword v176, v[148:149], off offset:512
	global_load_dword v177, v[148:149], off offset:576
	global_load_dword v178, v[148:149], off offset:640
	global_load_dword v179, v[148:149], off offset:704
	v_mov_b32_e32 v164, v124
	v_mov_b32_e32 v165, v116
	v_mov_b32_e32 v116, v125
	v_lshl_or_b32 v158, s5, 7, v151
	v_readlane_b32 s4, v255, 11
	v_readlane_b32 s5, v255, 12
	v_ashrrev_i32_e32 v159, 31, v158
	v_mov_b32_e32 v162, v122
	v_mov_b32_e32 v163, v114
	v_mov_b32_e32 v114, v123
	v_mov_b64_e32 v[122:123], s[4:5]
	v_mov_b32_e32 v160, v126
	v_mov_b32_e32 v161, v118
	v_mov_b32_e32 v118, v127
	v_mov_b32_e32 v126, v128
	v_mov_b32_e32 v127, v120
	v_mov_b32_e32 v120, v129
	v_mad_i64_i32 v[128:129], s[4:5], v146, s73, v[122:123]
	v_or_b32_e32 v166, 16, v146
	v_ashrrev_i32_e32 v167, 31, v166
	s_waitcnt vmcnt(0)
	v_fmamk_f32 v124, v147, 0x3a000000, v155
	v_rsq_f32_e32 v253, v124
	s_nop 1
	v_lshlrev_b64 v[124:125], 1, v[158:159]
	v_lshl_add_u64 v[128:129], v[128:129], 0, v[124:125]
	s_nop 1
	s_nop 1
	v_lshl_add_u64 v[158:159], v[166:167], 2, s[6:7]
	s_nop 0
	s_nop 0
	v_mov_b32_e32 v168, v253
	v_pk_mul_f32 v[118:119], v[118:119], v[168:169] op_sel_hi:[1,0]
	v_pk_mul_f32 v[114:115], v[114:115], v[168:169] op_sel_hi:[1,0]
	v_pk_mul_f32 v[126:127], v[126:127], v[168:169] op_sel_hi:[1,0]
	v_pk_mul_f32 v[116:117], v[116:117], v[168:169] op_sel_hi:[1,0]
	v_pk_mul_f32 v[160:161], v[160:161], v[168:169] op_sel_hi:[1,0]
	v_pk_mul_f32 v[162:163], v[162:163], v[168:169] op_sel_hi:[1,0]
	v_pk_mul_f32 v[164:165], v[164:165], v[168:169] op_sel_hi:[1,0]
	v_pk_mul_f32 v[120:121], v[120:121], v[168:169] op_sel_hi:[1,0]
	v_mul_f32_e32 v167, 0xbfb8aa3b, v119
	v_mul_f32_e32 v168, 0xbfb8aa3b, v115
	v_mul_f32_e32 v169, 0xbfb8aa3b, v127
	v_mul_f32_e32 v172, 0xbfb8aa3b, v117
	v_mul_f32_e32 v147, 0xbfb8aa3b, v161
	v_mul_f32_e32 v157, 0xbfb8aa3b, v163
	v_mul_f32_e32 v170, 0xbfb8aa3b, v165
	v_mul_f32_e32 v171, 0xbfb8aa3b, v121
	v_exp_f32_e32 v167, v167
	v_exp_f32_e32 v168, v168
	v_exp_f32_e32 v169, v169
	v_exp_f32_e32 v172, v172
	v_exp_f32_e32 v147, v147
	v_exp_f32_e32 v157, v157
	v_exp_f32_e32 v170, v170
	v_exp_f32_e32 v171, v171
	v_add_f32_e32 v167, 1.0, v167
	v_add_f32_e32 v168, 1.0, v168
	v_add_f32_e32 v169, 1.0, v169
	v_add_f32_e32 v172, 1.0, v172
	v_add_f32_e32 v147, 1.0, v147
	v_add_f32_e32 v157, 1.0, v157
	v_add_f32_e32 v170, 1.0, v170
	v_add_f32_e32 v171, 1.0, v171
	v_rcp_f32_e32 v167, v167
	v_rcp_f32_e32 v168, v168
	v_rcp_f32_e32 v169, v169
	v_rcp_f32_e32 v172, v172
	v_rcp_f32_e32 v147, v147
	v_rcp_f32_e32 v157, v157
	v_rcp_f32_e32 v170, v170
	v_rcp_f32_e32 v171, v171
	v_mul_f32_e32 v119, v119, v167
	v_mul_f32_e32 v115, v115, v168
	v_mul_f32_e32 v127, v127, v169
	v_mul_f32_e32 v117, v117, v172
	v_mul_f32_e32 v147, v161, v147
	v_mul_f32_e32 v157, v163, v157
	v_mul_f32_e32 v161, v165, v170
	v_mul_f32_e32 v121, v121, v171
	v_mul_f32_e32 v118, v118, v119
	v_mul_f32_e32 v119, v114, v115
	v_mul_f32_e32 v115, v126, v127
	v_mul_f32_e32 v117, v116, v117
	v_mul_f32_e32 v147, v160, v147
	v_mul_f32_e32 v157, v162, v157
	v_mul_f32_e32 v126, v164, v161
	v_mul_f32_e32 v120, v120, v121
	v_cvt_pk_bf16_f32 v114, v147, v118
	v_cvt_pk_bf16_f32 v115, v115, v120
	v_cvt_pk_bf16_f32 v116, v157, v119
	v_cvt_pk_bf16_f32 v117, v126, v117
	global_store_dwordx4 v[128:129], v[114:117], off
	s_nop 1
	v_mov_b32_e32 v118, v173
	s_nop 0
	v_mov_b32_e32 v115, v102
	v_mov_b32_e32 v102, v111
	v_mov_b32_e32 v111, v100
	v_mov_b32_e32 v100, v109
	v_mov_b32_e32 v116, v106
	v_mov_b32_e32 v106, v112
	v_mov_b32_e32 v117, v98
	v_mov_b32_e32 v98, v107
	v_mov_b32_e32 v107, v104
	v_mov_b32_e32 v104, v113
	v_mov_b32_e32 v114, v110
	v_mov_b32_e32 v110, v108
	v_or_b32_e32 v108, 32, v146
	v_fmamk_f32 v109, v118, 0x3a000000, v155
	v_rsq_f32_e32 v253, v109
	s_nop 1
	v_mad_i64_i32 v[112:113], s[4:5], v166, s73, v[122:123]
	v_ashrrev_i32_e32 v109, 31, v108
	v_lshl_add_u64 v[112:113], v[112:113], 0, v[124:125]
	s_nop 0
	s_nop 1
	s_nop 1
	v_lshl_add_u64 v[118:119], v[108:109], 2, s[6:7]
	s_nop 0
	v_mov_b32_e32 v120, v253
	v_pk_mul_f32 v[102:103], v[102:103], v[120:121] op_sel_hi:[1,0]
	v_pk_mul_f32 v[98:99], v[98:99], v[120:121] op_sel_hi:[1,0]
	v_pk_mul_f32 v[106:107], v[106:107], v[120:121] op_sel_hi:[1,0]
	v_pk_mul_f32 v[100:101], v[100:101], v[120:121] op_sel_hi:[1,0]
	v_pk_mul_f32 v[114:115], v[114:115], v[120:121] op_sel_hi:[1,0]
	v_pk_mul_f32 v[116:117], v[116:117], v[120:121] op_sel_hi:[1,0]
	v_pk_mul_f32 v[110:111], v[110:111], v[120:121] op_sel_hi:[1,0]
	v_pk_mul_f32 v[104:105], v[104:105], v[120:121] op_sel_hi:[1,0]
	v_mul_f32_e32 v121, 0xbfb8aa3b, v103
	v_mul_f32_e32 v126, 0xbfb8aa3b, v99
	v_mul_f32_e32 v127, 0xbfb8aa3b, v107
	v_mul_f32_e32 v147, 0xbfb8aa3b, v101
	v_mul_f32_e32 v109, 0xbfb8aa3b, v115
	v_mul_f32_e32 v120, 0xbfb8aa3b, v117
	v_mul_f32_e32 v128, 0xbfb8aa3b, v111
	v_mul_f32_e32 v129, 0xbfb8aa3b, v105
	v_exp_f32_e32 v121, v121
	v_exp_f32_e32 v126, v126
	v_exp_f32_e32 v127, v127
	v_exp_f32_e32 v147, v147
	v_exp_f32_e32 v109, v109
	v_exp_f32_e32 v120, v120
	v_exp_f32_e32 v128, v128
	v_exp_f32_e32 v129, v129
	v_add_f32_e32 v121, 1.0, v121
	v_add_f32_e32 v126, 1.0, v126
	v_add_f32_e32 v127, 1.0, v127
	v_add_f32_e32 v147, 1.0, v147
	v_add_f32_e32 v109, 1.0, v109
	v_add_f32_e32 v120, 1.0, v120
	v_add_f32_e32 v128, 1.0, v128
	v_add_f32_e32 v129, 1.0, v129
	v_rcp_f32_e32 v121, v121
; __device__ __forceinline__ float sigm(float x) { return __builtin_amdgcn_rcpf(1.f + __builtin_amdgcn_exp2f(-1.4426950408889634f * x)); }
; __device__ __forceinline__ void st8(bf16_t* p, const f32x4& a, const f32x4& b) { u32x4 w; w.x = pk2(a[0], a[1]); w.y = pk2(a[2], a[3]); w.z = pk2(b[0], b[1]); w.w = pk2(b[2], b[3]); *(u32x4*)p = w; }
;     __device__ __forceinline__ void operator()(const f32x4 (&acc)[2][2][4][2], const Unit& u, int wr, int wc, int fr, int fq) const {
;         const int row0 = u.pm * 256 + wr * 64 + fr, col0 = u.pn * 128 + wc * 32 + 8 * fq;
; #pragma unroll
;         for (int ai = 0; ai < 2; ++ai)
; #pragma unroll
;             for (int m = 0; m < 4; ++m) {
;                 const int row = row0 + ai * 128 + m * 16; const float rs = 1.0f / sqrtf(ssq[row] * (1.f / D) + RMS_EPS);
;                 f32x4 v0, v1;
; #pragma unroll
;                 for (int e = 0; e < 4; ++e) { const float g0 = acc[ai][0][m][0][e] * rs, g1 = acc[ai][0][m][1][e] * rs;
;                     v0[e] = g0 * sigm(g0) * (acc[ai][1][m][0][e] * rs); v1[e] = g1 * sigm(g1) * (acc[ai][1][m][1][e] * rs); }
;                 st8(O + (size_t)row * DFF + col0, v0, v1);
;             }
;     }
	v_rcp_f32_e32 v126, v126
	v_rcp_f32_e32 v127, v127
	v_rcp_f32_e32 v147, v147
	v_rcp_f32_e32 v109, v109
	v_rcp_f32_e32 v120, v120
	v_rcp_f32_e32 v128, v128
	v_rcp_f32_e32 v129, v129
	v_mul_f32_e32 v103, v103, v121
	v_mul_f32_e32 v99, v99, v126
	v_mul_f32_e32 v107, v107, v127
	v_mul_f32_e32 v101, v101, v147
	v_mul_f32_e32 v109, v115, v109
	v_mul_f32_e32 v115, v117, v120
	v_mul_f32_e32 v111, v111, v128
	v_mul_f32_e32 v105, v105, v129
	v_mul_f32_e32 v102, v102, v103
	v_mul_f32_e32 v103, v98, v99
	v_mul_f32_e32 v99, v106, v107
	v_mul_f32_e32 v101, v100, v101
	v_mul_f32_e32 v109, v114, v109
	v_mul_f32_e32 v114, v116, v115
	v_mul_f32_e32 v106, v110, v111
	v_mul_f32_e32 v104, v104, v105
	v_cvt_pk_bf16_f32 v98, v109, v102
	v_cvt_pk_bf16_f32 v99, v99, v104
	v_cvt_pk_bf16_f32 v100, v114, v103
	v_cvt_pk_bf16_f32 v101, v106, v101
	global_store_dwordx4 v[112:113], v[98:101], off
	s_nop 1
	v_mov_b32_e32 v102, v174
	s_nop 0
	v_mov_b32_e32 v99, v86
	v_mov_b32_e32 v86, v95
	v_mov_b32_e32 v95, v84
	v_mov_b32_e32 v84, v93
	v_mov_b32_e32 v100, v90
	v_mov_b32_e32 v90, v96
	v_mov_b32_e32 v101, v82
	v_mov_b32_e32 v82, v91
	v_mov_b32_e32 v91, v88
	v_mov_b32_e32 v88, v97
	v_mov_b32_e32 v98, v94
	v_mov_b32_e32 v94, v92
	v_or_b32_e32 v92, 48, v146
	v_fmamk_f32 v93, v102, 0x3a000000, v155
	v_rsq_f32_e32 v253, v93
	s_nop 1
	v_mad_i64_i32 v[96:97], s[4:5], v108, s73, v[122:123]
	v_ashrrev_i32_e32 v93, 31, v92
	v_lshl_add_u64 v[96:97], v[96:97], 0, v[124:125]
	s_nop 0
	s_nop 1
	s_nop 1
	v_lshl_add_u64 v[102:103], v[92:93], 2, s[6:7]
	s_nop 0
	v_mov_b32_e32 v104, v253
	v_pk_mul_f32 v[86:87], v[86:87], v[104:105] op_sel_hi:[1,0]
	v_pk_mul_f32 v[82:83], v[82:83], v[104:105] op_sel_hi:[1,0]
	v_pk_mul_f32 v[90:91], v[90:91], v[104:105] op_sel_hi:[1,0]
	v_pk_mul_f32 v[84:85], v[84:85], v[104:105] op_sel_hi:[1,0]
	v_pk_mul_f32 v[98:99], v[98:99], v[104:105] op_sel_hi:[1,0]
	v_pk_mul_f32 v[100:101], v[100:101], v[104:105] op_sel_hi:[1,0]
	v_pk_mul_f32 v[94:95], v[94:95], v[104:105] op_sel_hi:[1,0]
	v_pk_mul_f32 v[88:89], v[88:89], v[104:105] op_sel_hi:[1,0]
	v_mul_f32_e32 v105, 0xbfb8aa3b, v87
	v_mul_f32_e32 v106, 0xbfb8aa3b, v83
	v_mul_f32_e32 v107, 0xbfb8aa3b, v91
	v_mul_f32_e32 v110, 0xbfb8aa3b, v85
	v_mul_f32_e32 v93, 0xbfb8aa3b, v99
	v_mul_f32_e32 v104, 0xbfb8aa3b, v101
	v_mul_f32_e32 v108, 0xbfb8aa3b, v95
	v_mul_f32_e32 v109, 0xbfb8aa3b, v89
	v_exp_f32_e32 v105, v105
	v_exp_f32_e32 v106, v106
	v_exp_f32_e32 v107, v107
	v_exp_f32_e32 v110, v110
	v_exp_f32_e32 v93, v93
	v_exp_f32_e32 v104, v104
	v_exp_f32_e32 v108, v108
	v_exp_f32_e32 v109, v109
	v_add_f32_e32 v105, 1.0, v105
	v_add_f32_e32 v106, 1.0, v106
	v_add_f32_e32 v107, 1.0, v107
	v_add_f32_e32 v110, 1.0, v110
	v_add_f32_e32 v93, 1.0, v93
	v_add_f32_e32 v104, 1.0, v104
	v_add_f32_e32 v108, 1.0, v108
	v_add_f32_e32 v109, 1.0, v109
	v_rcp_f32_e32 v105, v105
	v_rcp_f32_e32 v106, v106
	v_rcp_f32_e32 v107, v107
	v_rcp_f32_e32 v110, v110
	v_rcp_f32_e32 v93, v93
	v_rcp_f32_e32 v104, v104
	v_rcp_f32_e32 v108, v108
	v_rcp_f32_e32 v109, v109
	v_mul_f32_e32 v87, v87, v105
	v_mul_f32_e32 v83, v83, v106
	v_mul_f32_e32 v91, v91, v107
	v_mul_f32_e32 v85, v85, v110
	v_mul_f32_e32 v93, v99, v93
	v_mul_f32_e32 v99, v101, v104
	v_mul_f32_e32 v95, v95, v108
	v_mul_f32_e32 v89, v89, v109
	v_mul_f32_e32 v86, v86, v87
	v_mul_f32_e32 v87, v82, v83
	v_mul_f32_e32 v83, v90, v91
	v_mul_f32_e32 v85, v84, v85
	v_mul_f32_e32 v93, v98, v93
	v_mul_f32_e32 v98, v100, v99
	v_mul_f32_e32 v90, v94, v95
	v_mul_f32_e32 v88, v88, v89
	v_cvt_pk_bf16_f32 v82, v93, v86
	v_cvt_pk_bf16_f32 v83, v83, v88
	v_cvt_pk_bf16_f32 v84, v98, v87
	v_cvt_pk_bf16_f32 v85, v90, v85
	global_store_dwordx4 v[96:97], v[82:85], off
	s_nop 1
	v_mov_b32_e32 v86, v175
	s_nop 0
	v_mov_b32_e32 v83, v70
	v_mov_b32_e32 v70, v79
	v_mov_b32_e32 v79, v68
	v_mov_b32_e32 v82, v78
	v_mov_b32_e32 v78, v76
	v_mov_b32_e32 v84, v74
	v_mov_b32_e32 v74, v80
	v_mov_b32_e32 v85, v66
	v_mov_b32_e32 v66, v75
	v_mov_b32_e32 v75, v72
	v_mov_b32_e32 v72, v81
	v_fmamk_f32 v68, v86, 0x3a000000, v155
	v_rsq_f32_e32 v253, v68
	s_nop 1
	v_mov_b32_e32 v68, v77
	v_mad_i64_i32 v[76:77], s[4:5], v92, s73, v[122:123]
	v_lshl_add_u64 v[76:77], v[76:77], 0, v[124:125]
	s_nop 0
	s_nop 1
	s_nop 1
	s_nop 0
	v_mov_b32_e32 v80, v253
	v_pk_mul_f32 v[70:71], v[70:71], v[80:81] op_sel_hi:[1,0]
	v_pk_mul_f32 v[66:67], v[66:67], v[80:81] op_sel_hi:[1,0]
	v_pk_mul_f32 v[74:75], v[74:75], v[80:81] op_sel_hi:[1,0]
	v_pk_mul_f32 v[68:69], v[68:69], v[80:81] op_sel_hi:[1,0]
	v_pk_mul_f32 v[82:83], v[82:83], v[80:81] op_sel_hi:[1,0]
	v_pk_mul_f32 v[84:85], v[84:85], v[80:81] op_sel_hi:[1,0]
	v_pk_mul_f32 v[78:79], v[78:79], v[80:81] op_sel_hi:[1,0]
	v_pk_mul_f32 v[72:73], v[72:73], v[80:81] op_sel_hi:[1,0]
	v_mul_f32_e32 v86, 0xbfb8aa3b, v71
	v_mul_f32_e32 v87, 0xbfb8aa3b, v67
	v_mul_f32_e32 v88, 0xbfb8aa3b, v75
	v_mul_f32_e32 v91, 0xbfb8aa3b, v69
	v_mul_f32_e32 v80, 0xbfb8aa3b, v83
	v_mul_f32_e32 v81, 0xbfb8aa3b, v85
	v_mul_f32_e32 v89, 0xbfb8aa3b, v79
	v_mul_f32_e32 v90, 0xbfb8aa3b, v73
	v_exp_f32_e32 v86, v86
	v_exp_f32_e32 v87, v87
	v_exp_f32_e32 v88, v88
	v_exp_f32_e32 v91, v91
	v_exp_f32_e32 v80, v80
	v_exp_f32_e32 v81, v81
	v_exp_f32_e32 v89, v89
	v_exp_f32_e32 v90, v90
	v_add_f32_e32 v86, 1.0, v86
	v_add_f32_e32 v87, 1.0, v87
	v_add_f32_e32 v88, 1.0, v88
	v_add_f32_e32 v91, 1.0, v91
	v_add_f32_e32 v80, 1.0, v80
	v_add_f32_e32 v81, 1.0, v81
	v_add_f32_e32 v89, 1.0, v89
	v_add_f32_e32 v90, 1.0, v90
	v_rcp_f32_e32 v86, v86
	v_rcp_f32_e32 v87, v87
	v_rcp_f32_e32 v88, v88
	v_rcp_f32_e32 v91, v91
	v_rcp_f32_e32 v80, v80
	v_rcp_f32_e32 v81, v81
	v_rcp_f32_e32 v89, v89
	v_rcp_f32_e32 v90, v90
	v_mul_f32_e32 v71, v71, v86
; __device__ __forceinline__ float sigm(float x) { return __builtin_amdgcn_rcpf(1.f + __builtin_amdgcn_exp2f(-1.4426950408889634f * x)); }
; __device__ __forceinline__ void st8(bf16_t* p, const f32x4& a, const f32x4& b) { u32x4 w; w.x = pk2(a[0], a[1]); w.y = pk2(a[2], a[3]); w.z = pk2(b[0], b[1]); w.w = pk2(b[2], b[3]); *(u32x4*)p = w; }
;     __device__ __forceinline__ void operator()(const f32x4 (&acc)[2][2][4][2], const Unit& u, int wr, int wc, int fr, int fq) const {
;         const int row0 = u.pm * 256 + wr * 64 + fr, col0 = u.pn * 128 + wc * 32 + 8 * fq;
; #pragma unroll
;         for (int ai = 0; ai < 2; ++ai)
; #pragma unroll
;             for (int m = 0; m < 4; ++m) {
;                 const int row = row0 + ai * 128 + m * 16; const float rs = 1.0f / sqrtf(ssq[row] * (1.f / D) + RMS_EPS);
;                 f32x4 v0, v1;
; #pragma unroll
;                 for (int e = 0; e < 4; ++e) { const float g0 = acc[ai][0][m][0][e] * rs, g1 = acc[ai][0][m][1][e] * rs;
;                     v0[e] = g0 * sigm(g0) * (acc[ai][1][m][0][e] * rs); v1[e] = g1 * sigm(g1) * (acc[ai][1][m][1][e] * rs); }
;                 st8(O + (size_t)row * DFF + col0, v0, v1);
;             }
;     }
	v_mul_f32_e32 v67, v67, v87
	v_mul_f32_e32 v75, v75, v88
	v_mul_f32_e32 v69, v69, v91
	v_mul_f32_e32 v80, v83, v80
	v_mul_f32_e32 v81, v85, v81
	v_mul_f32_e32 v79, v79, v89
	v_mul_f32_e32 v73, v73, v90
	v_mul_f32_e32 v70, v70, v71
	v_mul_f32_e32 v71, v66, v67
	v_mul_f32_e32 v67, v74, v75
	v_mul_f32_e32 v69, v68, v69
	v_mul_f32_e32 v80, v82, v80
	v_mul_f32_e32 v81, v84, v81
	v_mul_f32_e32 v74, v78, v79
	v_mul_f32_e32 v72, v72, v73
	v_cvt_pk_bf16_f32 v66, v80, v70
	v_cvt_pk_bf16_f32 v67, v67, v72
	v_cvt_pk_bf16_f32 v68, v81, v71
	v_cvt_pk_bf16_f32 v69, v74, v69
	global_store_dwordx4 v[76:77], v[66:69], off
	s_nop 1
	v_mov_b32_e32 v70, v176
	s_nop 0
	v_mov_b32_e32 v66, v62
	v_mov_b32_e32 v62, v60
	v_mov_b32_e32 v67, v54
	v_mov_b32_e32 v54, v63
	v_mov_b32_e32 v63, v52
	v_mov_b32_e32 v52, v61
	v_mov_b32_e32 v68, v58
	v_mov_b32_e32 v58, v64
	v_mov_b32_e32 v69, v50
	v_mov_b32_e32 v50, v59
	v_mov_b32_e32 v59, v56
	v_mov_b32_e32 v56, v65
	v_fmamk_f32 v60, v70, 0x3a000000, v155
	v_rsq_f32_e32 v253, v60
	s_nop 1
	v_add_u32_e32 v60, 0x80, v146
	v_mad_i64_i32 v[60:61], s[4:5], v60, s73, v[122:123]
	v_lshl_add_u64 v[60:61], v[60:61], 0, v[124:125]
	s_nop 0
	s_nop 1
	s_nop 1
	s_nop 0
	v_mov_b32_e32 v64, v253
	v_pk_mul_f32 v[54:55], v[54:55], v[64:65] op_sel_hi:[1,0]
	v_pk_mul_f32 v[50:51], v[50:51], v[64:65] op_sel_hi:[1,0]
	v_pk_mul_f32 v[58:59], v[58:59], v[64:65] op_sel_hi:[1,0]
	v_pk_mul_f32 v[52:53], v[52:53], v[64:65] op_sel_hi:[1,0]
	v_pk_mul_f32 v[66:67], v[66:67], v[64:65] op_sel_hi:[1,0]
	v_pk_mul_f32 v[68:69], v[68:69], v[64:65] op_sel_hi:[1,0]
	v_pk_mul_f32 v[62:63], v[62:63], v[64:65] op_sel_hi:[1,0]
	v_pk_mul_f32 v[56:57], v[56:57], v[64:65] op_sel_hi:[1,0]
	v_mul_f32_e32 v70, 0xbfb8aa3b, v55
	v_mul_f32_e32 v71, 0xbfb8aa3b, v51
	v_mul_f32_e32 v72, 0xbfb8aa3b, v59
	v_mul_f32_e32 v75, 0xbfb8aa3b, v53
	v_mul_f32_e32 v64, 0xbfb8aa3b, v67
	v_mul_f32_e32 v65, 0xbfb8aa3b, v69
	v_mul_f32_e32 v73, 0xbfb8aa3b, v63
	v_mul_f32_e32 v74, 0xbfb8aa3b, v57
	v_exp_f32_e32 v70, v70
	v_exp_f32_e32 v71, v71
	v_exp_f32_e32 v72, v72
	v_exp_f32_e32 v75, v75
	v_exp_f32_e32 v64, v64
	v_exp_f32_e32 v65, v65
	v_exp_f32_e32 v73, v73
	v_exp_f32_e32 v74, v74
	v_add_f32_e32 v70, 1.0, v70
	v_add_f32_e32 v71, 1.0, v71
	v_add_f32_e32 v72, 1.0, v72
	v_add_f32_e32 v75, 1.0, v75
	v_add_f32_e32 v64, 1.0, v64
	v_add_f32_e32 v65, 1.0, v65
	v_add_f32_e32 v73, 1.0, v73
	v_add_f32_e32 v74, 1.0, v74
	v_rcp_f32_e32 v70, v70
	v_rcp_f32_e32 v71, v71
	v_rcp_f32_e32 v72, v72
	v_rcp_f32_e32 v75, v75
	v_rcp_f32_e32 v64, v64
	v_rcp_f32_e32 v65, v65
	v_rcp_f32_e32 v73, v73
	v_rcp_f32_e32 v74, v74
	v_mul_f32_e32 v55, v55, v70
	v_mul_f32_e32 v51, v51, v71
	v_mul_f32_e32 v59, v59, v72
	v_mul_f32_e32 v53, v53, v75
	v_mul_f32_e32 v64, v67, v64
	v_mul_f32_e32 v65, v69, v65
	v_mul_f32_e32 v63, v63, v73
	v_mul_f32_e32 v57, v57, v74
	v_mul_f32_e32 v54, v54, v55
	v_mul_f32_e32 v55, v50, v51
	v_mul_f32_e32 v51, v58, v59
	v_mul_f32_e32 v53, v52, v53
	v_mul_f32_e32 v64, v66, v64
	v_mul_f32_e32 v65, v68, v65
	v_mul_f32_e32 v58, v62, v63
	v_mul_f32_e32 v56, v56, v57
	v_cvt_pk_bf16_f32 v50, v64, v54
	v_cvt_pk_bf16_f32 v51, v51, v56
	v_cvt_pk_bf16_f32 v52, v65, v55
	v_cvt_pk_bf16_f32 v53, v58, v53
	global_store_dwordx4 v[60:61], v[50:53], off
	s_nop 1
	v_mov_b32_e32 v54, v177
	s_nop 0
	v_mov_b32_e32 v50, v46
	v_mov_b32_e32 v46, v44
	v_mov_b32_e32 v51, v38
	v_mov_b32_e32 v38, v47
	v_mov_b32_e32 v47, v36
	v_mov_b32_e32 v36, v45
	v_mov_b32_e32 v52, v42
	v_mov_b32_e32 v42, v48
	v_mov_b32_e32 v53, v34
	v_mov_b32_e32 v34, v43
	v_mov_b32_e32 v43, v40
	v_mov_b32_e32 v40, v49
	v_fmamk_f32 v44, v54, 0x3a000000, v155
	v_rsq_f32_e32 v253, v44
	s_nop 1
	v_add_u32_e32 v44, 0x90, v146
	v_mad_i64_i32 v[44:45], s[4:5], v44, s73, v[122:123]
	v_lshl_add_u64 v[44:45], v[44:45], 0, v[124:125]
	s_nop 0
	s_nop 1
	s_nop 1
	s_nop 0
	v_mov_b32_e32 v48, v253
	v_pk_mul_f32 v[38:39], v[38:39], v[48:49] op_sel_hi:[1,0]
	v_pk_mul_f32 v[34:35], v[34:35], v[48:49] op_sel_hi:[1,0]
	v_pk_mul_f32 v[42:43], v[42:43], v[48:49] op_sel_hi:[1,0]
	v_pk_mul_f32 v[36:37], v[36:37], v[48:49] op_sel_hi:[1,0]
	v_pk_mul_f32 v[50:51], v[50:51], v[48:49] op_sel_hi:[1,0]
	v_pk_mul_f32 v[52:53], v[52:53], v[48:49] op_sel_hi:[1,0]
	v_pk_mul_f32 v[46:47], v[46:47], v[48:49] op_sel_hi:[1,0]
	v_pk_mul_f32 v[40:41], v[40:41], v[48:49] op_sel_hi:[1,0]
	v_mul_f32_e32 v54, 0xbfb8aa3b, v39
	v_mul_f32_e32 v55, 0xbfb8aa3b, v35
	v_mul_f32_e32 v56, 0xbfb8aa3b, v43
	v_mul_f32_e32 v59, 0xbfb8aa3b, v37
	v_mul_f32_e32 v48, 0xbfb8aa3b, v51
	v_mul_f32_e32 v49, 0xbfb8aa3b, v53
	v_mul_f32_e32 v57, 0xbfb8aa3b, v47
	v_mul_f32_e32 v58, 0xbfb8aa3b, v41
	v_exp_f32_e32 v54, v54
	v_exp_f32_e32 v55, v55
	v_exp_f32_e32 v56, v56
	v_exp_f32_e32 v59, v59
	v_exp_f32_e32 v48, v48
	v_exp_f32_e32 v49, v49
	v_exp_f32_e32 v57, v57
	v_exp_f32_e32 v58, v58
	v_add_f32_e32 v54, 1.0, v54
	v_add_f32_e32 v55, 1.0, v55
	v_add_f32_e32 v56, 1.0, v56
	v_add_f32_e32 v59, 1.0, v59
	v_add_f32_e32 v48, 1.0, v48
	v_add_f32_e32 v49, 1.0, v49
	v_add_f32_e32 v57, 1.0, v57
	v_add_f32_e32 v58, 1.0, v58
	v_rcp_f32_e32 v54, v54
	v_rcp_f32_e32 v55, v55
	v_rcp_f32_e32 v56, v56
	v_rcp_f32_e32 v59, v59
	v_rcp_f32_e32 v48, v48
	v_rcp_f32_e32 v49, v49
	v_rcp_f32_e32 v57, v57
	v_rcp_f32_e32 v58, v58
	v_mul_f32_e32 v39, v39, v54
	v_mul_f32_e32 v35, v35, v55
	v_mul_f32_e32 v43, v43, v56
	v_mul_f32_e32 v37, v37, v59
	v_mul_f32_e32 v48, v51, v48
	v_mul_f32_e32 v49, v53, v49
	v_mul_f32_e32 v47, v47, v57
	v_mul_f32_e32 v41, v41, v58
	v_mul_f32_e32 v38, v38, v39
	v_mul_f32_e32 v39, v34, v35
	v_mul_f32_e32 v35, v42, v43
	v_mul_f32_e32 v37, v36, v37
	v_mul_f32_e32 v48, v50, v48
	v_mul_f32_e32 v49, v52, v49
; __device__ __forceinline__ float sigm(float x) { return __builtin_amdgcn_rcpf(1.f + __builtin_amdgcn_exp2f(-1.4426950408889634f * x)); }
; __device__ __forceinline__ void st8(bf16_t* p, const f32x4& a, const f32x4& b) { u32x4 w; w.x = pk2(a[0], a[1]); w.y = pk2(a[2], a[3]); w.z = pk2(b[0], b[1]); w.w = pk2(b[2], b[3]); *(u32x4*)p = w; }
;     __device__ __forceinline__ void operator()(const f32x4 (&acc)[2][2][4][2], const Unit& u, int wr, int wc, int fr, int fq) const {
;     ...
;                 const int row = row0 + ai * 128 + m * 16; const float rs = 1.0f / sqrtf(ssq[row] * (1.f / D) + RMS_EPS);
;                 f32x4 v0, v1;
; #pragma unroll
;                 for (int e = 0; e < 4; ++e) { const float g0 = acc[ai][0][m][0][e] * rs, g1 = acc[ai][0][m][1][e] * rs;
;                     v0[e] = g0 * sigm(g0) * (acc[ai][1][m][0][e] * rs); v1[e] = g1 * sigm(g1) * (acc[ai][1][m][1][e] * rs); }
;                 st8(O + (size_t)row * DFF + col0, v0, v1);
	v_mul_f32_e32 v42, v46, v47
	v_mul_f32_e32 v40, v40, v41
	v_cvt_pk_bf16_f32 v34, v48, v38
	v_cvt_pk_bf16_f32 v35, v35, v40
	v_cvt_pk_bf16_f32 v36, v49, v39
	v_cvt_pk_bf16_f32 v37, v42, v37
	global_store_dwordx4 v[44:45], v[34:37], off
	s_nop 1
	v_mov_b32_e32 v38, v178
	s_nop 0
	v_mov_b32_e32 v34, v30
	v_mov_b32_e32 v30, v28
	v_mov_b32_e32 v35, v22
	v_mov_b32_e32 v22, v31
	v_mov_b32_e32 v31, v20
	v_mov_b32_e32 v20, v29
	v_mov_b32_e32 v36, v26
	v_mov_b32_e32 v26, v32
	v_mov_b32_e32 v37, v18
	v_mov_b32_e32 v18, v27
	v_mov_b32_e32 v27, v24
	v_mov_b32_e32 v24, v33
	v_fmamk_f32 v28, v38, 0x3a000000, v155
	v_rsq_f32_e32 v253, v28
	s_nop 1
	v_add_u32_e32 v28, 0xa0, v146
	v_mad_i64_i32 v[28:29], s[4:5], v28, s73, v[122:123]
	v_lshl_add_u64 v[28:29], v[28:29], 0, v[124:125]
	s_nop 0
	s_nop 1
	s_nop 1
	s_nop 0
	v_mov_b32_e32 v32, v253
	v_pk_mul_f32 v[22:23], v[22:23], v[32:33] op_sel_hi:[1,0]
	v_pk_mul_f32 v[18:19], v[18:19], v[32:33] op_sel_hi:[1,0]
	v_pk_mul_f32 v[26:27], v[26:27], v[32:33] op_sel_hi:[1,0]
	v_pk_mul_f32 v[20:21], v[20:21], v[32:33] op_sel_hi:[1,0]
	v_pk_mul_f32 v[34:35], v[34:35], v[32:33] op_sel_hi:[1,0]
	v_pk_mul_f32 v[36:37], v[36:37], v[32:33] op_sel_hi:[1,0]
	v_pk_mul_f32 v[30:31], v[30:31], v[32:33] op_sel_hi:[1,0]
	v_pk_mul_f32 v[24:25], v[24:25], v[32:33] op_sel_hi:[1,0]
	v_mul_f32_e32 v38, 0xbfb8aa3b, v23
	v_mul_f32_e32 v39, 0xbfb8aa3b, v19
	v_mul_f32_e32 v40, 0xbfb8aa3b, v27
	v_mul_f32_e32 v43, 0xbfb8aa3b, v21
	v_mul_f32_e32 v32, 0xbfb8aa3b, v35
	v_mul_f32_e32 v33, 0xbfb8aa3b, v37
	v_mul_f32_e32 v41, 0xbfb8aa3b, v31
	v_mul_f32_e32 v42, 0xbfb8aa3b, v25
	v_exp_f32_e32 v38, v38
	v_exp_f32_e32 v39, v39
	v_exp_f32_e32 v40, v40
	v_exp_f32_e32 v43, v43
	v_exp_f32_e32 v32, v32
	v_exp_f32_e32 v33, v33
	v_exp_f32_e32 v41, v41
	v_exp_f32_e32 v42, v42
	v_add_f32_e32 v38, 1.0, v38
	v_add_f32_e32 v39, 1.0, v39
	v_add_f32_e32 v40, 1.0, v40
	v_add_f32_e32 v43, 1.0, v43
	v_add_f32_e32 v32, 1.0, v32
	v_add_f32_e32 v33, 1.0, v33
	v_add_f32_e32 v41, 1.0, v41
	v_add_f32_e32 v42, 1.0, v42
	v_rcp_f32_e32 v38, v38
	v_rcp_f32_e32 v39, v39
	v_rcp_f32_e32 v40, v40
	v_rcp_f32_e32 v43, v43
	v_rcp_f32_e32 v32, v32
	v_rcp_f32_e32 v33, v33
	v_rcp_f32_e32 v41, v41
	v_rcp_f32_e32 v42, v42
	v_mul_f32_e32 v23, v23, v38
	v_mul_f32_e32 v19, v19, v39
	v_mul_f32_e32 v27, v27, v40
	v_mul_f32_e32 v21, v21, v43
	v_mul_f32_e32 v32, v35, v32
	v_mul_f32_e32 v33, v37, v33
	v_mul_f32_e32 v31, v31, v41
	v_mul_f32_e32 v25, v25, v42
	v_mul_f32_e32 v22, v22, v23
	v_mul_f32_e32 v23, v18, v19
	v_mul_f32_e32 v19, v26, v27
	v_mul_f32_e32 v21, v20, v21
	v_mul_f32_e32 v32, v34, v32
	v_mul_f32_e32 v33, v36, v33
	v_mul_f32_e32 v26, v30, v31
	v_mul_f32_e32 v24, v24, v25
	v_cvt_pk_bf16_f32 v18, v32, v22
	v_cvt_pk_bf16_f32 v19, v19, v24
	v_cvt_pk_bf16_f32 v20, v33, v23
	v_cvt_pk_bf16_f32 v21, v26, v21
	global_store_dwordx4 v[28:29], v[18:21], off
	s_nop 1
	v_mov_b32_e32 v22, v179
	s_nop 0
	v_mov_b32_e32 v19, v6
	v_mov_b32_e32 v6, v15
	v_mov_b32_e32 v15, v4
	v_mov_b32_e32 v4, v13
	v_mov_b32_e32 v20, v10
	v_mov_b32_e32 v10, v16
	v_mov_b32_e32 v21, v2
	v_mov_b32_e32 v2, v11
	v_mov_b32_e32 v11, v8
	v_mov_b32_e32 v8, v17
	v_mov_b32_e32 v18, v14
	v_mov_b32_e32 v14, v12
	v_add_u32_e32 v12, 0xb0, v146
	v_fmamk_f32 v13, v22, 0x3a000000, v155
	v_rsq_f32_e32 v253, v13
	s_nop 1
	v_mad_i64_i32 v[12:13], s[4:5], v12, s73, v[122:123]
	v_lshl_add_u64 v[12:13], v[12:13], 0, v[124:125]
	s_nop 1
	s_nop 1
	s_nop 1
	s_nop 0
	v_mov_b32_e32 v16, v253
	v_pk_mul_f32 v[6:7], v[6:7], v[16:17] op_sel_hi:[1,0]
	v_pk_mul_f32 v[2:3], v[2:3], v[16:17] op_sel_hi:[1,0]
	v_pk_mul_f32 v[10:11], v[10:11], v[16:17] op_sel_hi:[1,0]
	v_pk_mul_f32 v[4:5], v[4:5], v[16:17] op_sel_hi:[1,0]
	v_pk_mul_f32 v[18:19], v[18:19], v[16:17] op_sel_hi:[1,0]
	v_pk_mul_f32 v[20:21], v[20:21], v[16:17] op_sel_hi:[1,0]
	v_pk_mul_f32 v[14:15], v[14:15], v[16:17] op_sel_hi:[1,0]
	v_pk_mul_f32 v[8:9], v[8:9], v[16:17] op_sel_hi:[1,0]
	v_mul_f32_e32 v22, 0xbfb8aa3b, v7
	v_mul_f32_e32 v23, 0xbfb8aa3b, v3
	v_mul_f32_e32 v24, 0xbfb8aa3b, v11
	v_mul_f32_e32 v27, 0xbfb8aa3b, v5
	v_mul_f32_e32 v16, 0xbfb8aa3b, v19
	v_mul_f32_e32 v17, 0xbfb8aa3b, v21
	v_mul_f32_e32 v25, 0xbfb8aa3b, v15
	v_mul_f32_e32 v26, 0xbfb8aa3b, v9
	v_exp_f32_e32 v22, v22
	v_exp_f32_e32 v23, v23
	v_exp_f32_e32 v24, v24
	v_exp_f32_e32 v27, v27
	v_exp_f32_e32 v16, v16
	v_exp_f32_e32 v17, v17
	v_exp_f32_e32 v25, v25
	v_exp_f32_e32 v26, v26
	v_add_f32_e32 v22, 1.0, v22
	v_add_f32_e32 v23, 1.0, v23
	v_add_f32_e32 v24, 1.0, v24
	v_add_f32_e32 v27, 1.0, v27
	v_add_f32_e32 v16, 1.0, v16
	v_add_f32_e32 v17, 1.0, v17
	v_add_f32_e32 v25, 1.0, v25
	v_add_f32_e32 v26, 1.0, v26
	v_rcp_f32_e32 v22, v22
	v_rcp_f32_e32 v23, v23
	v_rcp_f32_e32 v24, v24
	v_rcp_f32_e32 v27, v27
	v_rcp_f32_e32 v16, v16
	v_rcp_f32_e32 v17, v17
	v_rcp_f32_e32 v25, v25
	v_rcp_f32_e32 v26, v26
	v_mul_f32_e32 v7, v7, v22
	v_mul_f32_e32 v3, v3, v23
	v_mul_f32_e32 v11, v11, v24
	v_mul_f32_e32 v5, v5, v27
	s_andn2_b64 vcc, exec, s[2:3]
	v_mul_f32_e32 v16, v19, v16
	v_mul_f32_e32 v17, v21, v17
	v_mul_f32_e32 v15, v15, v25
	v_mul_f32_e32 v9, v9, v26
	v_mul_f32_e32 v6, v6, v7
	v_mul_f32_e32 v7, v2, v3
	v_mul_f32_e32 v3, v10, v11
	v_mul_f32_e32 v5, v4, v5
	s_mov_b64 s[2:3], -1
	v_mul_f32_e32 v16, v18, v16
	v_mul_f32_e32 v17, v20, v17
	v_mul_f32_e32 v10, v14, v15
	v_mul_f32_e32 v8, v8, v9
	v_cvt_pk_bf16_f32 v2, v16, v6
	v_cvt_pk_bf16_f32 v3, v3, v8
	v_cvt_pk_bf16_f32 v4, v17, v7
	v_cvt_pk_bf16_f32 v5, v10, v5
	global_store_dwordx4 v[12:13], v[2:5], off
	s_cbranch_vccnz .LBB0_1003
	s_andn2_b64 vcc, exec, s[36:37]
	s_cbranch_vccnz .LBB0_1002
	s_barrier
	s_branch .LBB0_1002
